# CONV: next 16-row batch prefetched into spare regs during current batch compute (counted vmcnt(16), raw-row waits only on sample path)
# baseline (speedup 1.0000x reference)
; __device__ __forceinline__ float bflo(unsigned w) { return __uint_as_float(w << 16); }
; __device__ __forceinline__ float bfhi(unsigned w) { return __uint_as_float(w & 0xffff0000u); }
; __device__ __forceinline__ void conv_phase(const Ctx& c) {
;     ...
;             const int ck = it / 12, sl = it % 12, ch = sl * 256 + c.lane * 4;
;             const f32x4 w0 = *(const f32x4*)(cw + ch), w1 = *(const f32x4*)(cw + CONVD + ch), w2 = *(const f32x4*)(cw + 2 * CONVD + ch), w3 = *(const f32x4*)(cw + 3 * CONVD + ch);
;             const f32x4 bb = *(const f32x4*)(cbias + ch);
;             const bool samp = ck >= 256;
;             f32x4 h0 = (f32x4){0.f, 0.f, 0.f, 0.f}, h1 = h0, h2 = h0;
;             if (!samp && (ck & 31) != 0) {
;                 const bf16_t* hp = HALO + (size_t)(ck - 1) * 3 * CONVD + ch;
;                 const u32x2 a = *(const u32x2*)hp, b = *(const u32x2*)(hp + CONVD), d = *(const u32x2*)(hp + 2 * CONVD);
;                 h0 = (f32x4){bflo(a.x), bfhi(a.x), bflo(a.y), bfhi(a.y)}; h1 = (f32x4){bflo(b.x), bfhi(b.x), bflo(b.y), bfhi(b.y)}; h2 = (f32x4){bflo(d.x), bfhi(d.x), bflo(d.y), bfhi(d.y)};
;             }
;             const bool lastp = !samp && (ck & 31) == 31;
;             for (int t0 = 0; t0 < 128; t0 += 16) {
;                 const size_t rbase = (size_t)ck * 128 + t0;
;                 u32x2 raw[16];
; #pragma unroll
;                 for (int i = 0; i < 16; ++i) raw[i] = *(const u32x2*)(XBC + (rbase + i) * CONVD + ch);
.LBB0_244:
	s_cmp_eq_u32 s5, 31
	s_cselect_b64 s[14:15], -1, 0
	s_ashr_i32 s5, s4, 5
	v_lshl_add_u64 v[66:67], s[10:11], 0, v[72:73]
	s_mul_i32 s5, s5, 3
	s_lshl_b32 s6, s4, 4
	s_add_i32 s23, s6, 0xfffff000
	v_mad_i64_i32 v[66:67], s[6:7], s5, v229, v[66:67]
	s_mov_b64 s[6:7], 0x3000
	s_nop 0
	v_lshl_add_u64 v[68:69], v[66:67], 0, s[6:7]
	s_mov_b64 s[6:7], 0x6000
	v_lshl_add_u64 v[70:71], v[66:67], 0, s[6:7]
	s_mul_i32 s6, s23, 0x9000
	v_readlane_b32 s7, v253, 25
	s_mul_hi_i32 s5, s23, 0x9000
	s_add_u32 s6, s7, s6
	v_readlane_b32 s7, v253, 26
	s_addc_u32 s7, s7, s5
	s_mul_hi_i32 s5, s4, 0xc0000
	s_mul_i32 s4, s4, 0xc0000
	s_add_u32 s4, s90, s4
	s_addc_u32 s5, s91, s5
	v_lshl_add_u64 v[0:1], s[8:9], 0, v[72:73]
	v_lshl_add_u64 v[72:73], s[6:7], 0, v[72:73]
	v_lshl_add_u64 v[74:75], v[74:75], 1, s[4:5]
	s_mov_b64 s[6:7], 0x13488000
	s_nop 0
	v_lshl_add_u64 v[202:203], v[74:75], 0, s[6:7]
	s_mov_b64 s[6:7], 0x1000
	s_nop 0
	v_lshl_add_u64 v[204:205], v[202:203], 0, s[6:7]
	s_mov_b64 s[6:7], 0x3000
	global_load_dwordx2 v[170:171], v[202:203], off
	global_load_dwordx2 v[172:173], v[204:205], off offset:2048
	v_lshl_add_u64 v[202:203], v[202:203], 0, s[6:7]
	v_lshl_add_u64 v[204:205], v[204:205], 0, s[6:7]
	global_load_dwordx2 v[174:175], v[202:203], off
	global_load_dwordx2 v[176:177], v[204:205], off offset:2048
	v_lshl_add_u64 v[202:203], v[202:203], 0, s[6:7]
	v_lshl_add_u64 v[204:205], v[204:205], 0, s[6:7]
	global_load_dwordx2 v[178:179], v[202:203], off
	global_load_dwordx2 v[180:181], v[204:205], off offset:2048
	v_lshl_add_u64 v[202:203], v[202:203], 0, s[6:7]
	v_lshl_add_u64 v[204:205], v[204:205], 0, s[6:7]
	global_load_dwordx2 v[182:183], v[202:203], off
	global_load_dwordx2 v[184:185], v[204:205], off offset:2048
	v_lshl_add_u64 v[202:203], v[202:203], 0, s[6:7]
	v_lshl_add_u64 v[204:205], v[204:205], 0, s[6:7]
	global_load_dwordx2 v[186:187], v[202:203], off
	global_load_dwordx2 v[188:189], v[204:205], off offset:2048
	v_lshl_add_u64 v[202:203], v[202:203], 0, s[6:7]
	v_lshl_add_u64 v[204:205], v[204:205], 0, s[6:7]
	global_load_dwordx2 v[190:191], v[202:203], off
	global_load_dwordx2 v[192:193], v[204:205], off offset:2048
	v_lshl_add_u64 v[202:203], v[202:203], 0, s[6:7]
	v_lshl_add_u64 v[204:205], v[204:205], 0, s[6:7]
	global_load_dwordx2 v[194:195], v[202:203], off
	global_load_dwordx2 v[196:197], v[204:205], off offset:2048
	v_lshl_add_u64 v[202:203], v[202:203], 0, s[6:7]
	v_lshl_add_u64 v[204:205], v[204:205], 0, s[6:7]
	global_load_dwordx2 v[198:199], v[202:203], off
	global_load_dwordx2 v[200:201], v[204:205], off offset:2048
	s_waitcnt vmcnt(0)
	s_mov_b32 s24, -16
	s_mov_b64 s[16:17], 0
	v_readlane_b32 s26, v251, 58
	s_mov_b32 s88, s34
	v_readlane_b32 s27, v251, 59
	s_branch .LBB0_246

; __device__ __forceinline__ void conv_phase(const Ctx& c) {
;     ...
;             for (int t0 = 0; t0 < 128; t0 += 16) {
;                 const size_t rbase = (size_t)ck * 128 + t0;
;                 u32x2 raw[16];
; #pragma unroll
;                 for (int i = 0; i < 16; ++i) raw[i] = *(const u32x2*)(XBC + (rbase + i) * CONVD + ch);
.LBB0_246:
	s_waitcnt vmcnt(16)
	v_mov_b64_e32 v[122:123], v[170:171]
	v_mov_b64_e32 v[114:115], v[172:173]
	v_mov_b64_e32 v[110:111], v[174:175]
	v_mov_b64_e32 v[106:107], v[176:177]
	v_mov_b64_e32 v[102:103], v[178:179]
	v_mov_b64_e32 v[98:99], v[180:181]
	v_mov_b64_e32 v[96:97], v[182:183]
	v_mov_b64_e32 v[94:95], v[184:185]
	v_mov_b64_e32 v[92:93], v[186:187]
	v_mov_b64_e32 v[90:91], v[188:189]
	v_mov_b64_e32 v[88:89], v[190:191]
	v_mov_b64_e32 v[86:87], v[192:193]
	v_mov_b64_e32 v[84:85], v[194:195]
	v_mov_b64_e32 v[82:83], v[196:197]
	v_mov_b64_e32 v[80:81], v[198:199]
	v_mov_b64_e32 v[78:79], v[200:201]
	v_lshl_add_u64 v[76:77], v[74:75], 0, s[16:17]
	v_cndmask_b32_e64 v3, 0, 1, s[2:3]
	s_mov_b32 s25, 0
	v_cmp_ne_u32_e64 s[4:5], 1, v3
	s_cmpk_eq_i32 s24, 0x60
	s_cbranch_scc1 .Lconv_nopf
	s_mov_b64 s[6:7], 0x134a0000
	s_nop 0
	v_lshl_add_u64 v[202:203], v[76:77], 0, s[6:7]
	s_mov_b64 s[6:7], 0x1000
	s_nop 0
	v_lshl_add_u64 v[204:205], v[202:203], 0, s[6:7]
	s_mov_b64 s[6:7], 0x3000
	global_load_dwordx2 v[170:171], v[202:203], off
	global_load_dwordx2 v[172:173], v[204:205], off offset:2048
	v_lshl_add_u64 v[202:203], v[202:203], 0, s[6:7]
	v_lshl_add_u64 v[204:205], v[204:205], 0, s[6:7]
	global_load_dwordx2 v[174:175], v[202:203], off
	global_load_dwordx2 v[176:177], v[204:205], off offset:2048
	v_lshl_add_u64 v[202:203], v[202:203], 0, s[6:7]
	v_lshl_add_u64 v[204:205], v[204:205], 0, s[6:7]
	global_load_dwordx2 v[178:179], v[202:203], off
	global_load_dwordx2 v[180:181], v[204:205], off offset:2048
	v_lshl_add_u64 v[202:203], v[202:203], 0, s[6:7]
	v_lshl_add_u64 v[204:205], v[204:205], 0, s[6:7]
	global_load_dwordx2 v[182:183], v[202:203], off
	global_load_dwordx2 v[184:185], v[204:205], off offset:2048
	v_lshl_add_u64 v[202:203], v[202:203], 0, s[6:7]
	v_lshl_add_u64 v[204:205], v[204:205], 0, s[6:7]
	global_load_dwordx2 v[186:187], v[202:203], off
	global_load_dwordx2 v[188:189], v[204:205], off offset:2048
	v_lshl_add_u64 v[202:203], v[202:203], 0, s[6:7]
	v_lshl_add_u64 v[204:205], v[204:205], 0, s[6:7]
	global_load_dwordx2 v[190:191], v[202:203], off
	global_load_dwordx2 v[192:193], v[204:205], off offset:2048
	v_lshl_add_u64 v[202:203], v[202:203], 0, s[6:7]
	v_lshl_add_u64 v[204:205], v[204:205], 0, s[6:7]
	global_load_dwordx2 v[194:195], v[202:203], off
	global_load_dwordx2 v[196:197], v[204:205], off offset:2048
	v_lshl_add_u64 v[202:203], v[202:203], 0, s[6:7]
	v_lshl_add_u64 v[204:205], v[204:205], 0, s[6:7]
	global_load_dwordx2 v[198:199], v[202:203], off
	global_load_dwordx2 v[200:201], v[204:205], off offset:2048
.Lconv_nopf:
	s_andn2_b64 vcc, exec, s[2:3]
	s_cbranch_vccnz .LBB0_248
	v_add_co_u32_e32 v4, vcc, 0xffff7000, v72
	s_mov_b32 s25, s23
	s_nop 0
	v_addc_co_u32_e32 v5, vcc, -1, v73, vcc
	v_add_co_u32_e32 v8, vcc, 0xffffa000, v72
	global_load_dwordx4 v[4:7], v[4:5], off
	s_nop 0
	v_addc_co_u32_e32 v9, vcc, -1, v73, vcc
	v_add_co_u32_e32 v12, vcc, 0xffffd000, v72
	global_load_dwordx4 v[8:11], v[8:9], off
	s_nop 0
	v_addc_co_u32_e32 v13, vcc, -1, v73, vcc
	v_add_co_u32_e32 v20, vcc, 0x3000, v72
	global_load_dwordx4 v[12:15], v[12:13], off
	s_nop 0
	global_load_dwordx4 v[16:19], v[72:73], off
	v_addc_co_u32_e32 v21, vcc, 0, v73, vcc
	v_add_co_u32_e32 v24, vcc, 0x6000, v72
	global_load_dwordx4 v[20:23], v[20:21], off
	s_nop 0
	v_addc_co_u32_e32 v25, vcc, 0, v73, vcc
	global_load_dwordx4 v[24:27], v[24:25], off
.LBB0_248:
	s_cmp_lg_u64 s[2:3], 0
	s_cbranch_scc0 .Lconv_nw0
	s_waitcnt vmcnt(3)
.Lconv_nw0:
	v_cndmask_b32_e64 v119, v57, v13, s[2:3]
	v_cndmask_b32_e64 v118, v56, v12, s[2:3]
	v_cndmask_b32_e64 v57, v49, v5, s[2:3]
	v_cndmask_b32_e64 v56, v48, v4, s[2:3]
	v_cndmask_b32_e64 v53, v53, v9, s[2:3]
	v_cndmask_b32_e64 v52, v52, v8, s[2:3]
	v_pk_mul_f32 v[56:57], v[28:29], v[56:57]
	v_lshlrev_b32_e32 v48, 16, v122
	v_pk_fma_f32 v[56:57], v[32:33], v[52:53], v[56:57]
	v_and_b32_e32 v49, 0xffff0000, v122
	v_pk_fma_f32 v[56:57], v[36:37], v[118:119], v[56:57]
	v_cndmask_b32_e64 v121, v59, v15, s[2:3]
	v_pk_fma_f32 v[56:57], v[40:41], v[48:49], v[56:57]
	v_cndmask_b32_e64 v120, v58, v14, s[2:3]
	v_pk_add_f32 v[56:57], v[44:45], v[56:57]
	v_cndmask_b32_e64 v59, v51, v7, s[2:3]
	v_mul_f32_e32 v3, 0xbfb8aa3b, v56
	v_exp_f32_e32 v3, v3
	v_cndmask_b32_e64 v58, v50, v6, s[2:3]
	v_cndmask_b32_e64 v55, v55, v11, s[2:3]
	v_cndmask_b32_e64 v54, v54, v10, s[2:3]
	v_add_f32_e32 v3, 1.0, v3
	v_rcp_f32_e32 v122, v3
	v_mul_f32_e32 v3, 0xbfb8aa3b, v57
	v_pk_mul_f32 v[58:59], v[30:31], v[58:59]
	v_exp_f32_e32 v3, v3
	v_pk_fma_f32 v[58:59], v[34:35], v[54:55], v[58:59]
	v_lshlrev_b32_e32 v50, 16, v123
	v_and_b32_e32 v51, 0xffff0000, v123
	v_pk_fma_f32 v[58:59], v[38:39], v[120:121], v[58:59]
	v_add_f32_e32 v3, 1.0, v3
	v_pk_fma_f32 v[58:59], v[42:43], v[50:51], v[58:59]
	v_rcp_f32_e32 v123, v3
	v_pk_add_f32 v[58:59], v[46:47], v[58:59]
	s_mov_b64 s[6:7], 0x13488000
	v_mul_f32_e32 v3, 0xbfb8aa3b, v58
	v_exp_f32_e32 v3, v3
	v_pk_mul_f32 v[56:57], v[56:57], v[122:123]
	v_pk_mul_f32 v[52:53], v[28:29], v[52:53]
	v_lshl_add_u64 v[126:127], v[76:77], 0, s[6:7]
	v_add_f32_e32 v3, 1.0, v3
	v_rcp_f32_e32 v122, v3
	v_mul_f32_e32 v3, 0xbfb8aa3b, v59
	v_exp_f32_e32 v3, v3
	v_cvt_pk_bf16_f32 v56, v56, v57
	v_pk_fma_f32 v[52:53], v[32:33], v[118:119], v[52:53]
	v_pk_mul_f32 v[54:55], v[30:31], v[54:55]
	v_add_f32_e32 v3, 1.0, v3
	v_rcp_f32_e32 v123, v3
	v_pk_fma_f32 v[52:53], v[36:37], v[48:49], v[52:53]
	v_pk_fma_f32 v[54:55], v[34:35], v[120:121], v[54:55]
	s_mov_b64 s[6:7], 0x13489800
	v_pk_mul_f32 v[58:59], v[58:59], v[122:123]
	v_pk_fma_f32 v[54:55], v[38:39], v[50:51], v[54:55]
	v_cvt_pk_bf16_f32 v57, v58, v59
	global_store_dwordx2 v[126:127], v[56:57], off
; __device__ __forceinline__ unsigned cvt_pk_bf16(float lo, float hi) { f32x2 v = {lo, hi}; bf16x2_t b = __builtin_convertvector(v, bf16x2_t); return __builtin_bit_cast(unsigned, b); }
; __device__ __forceinline__ float bflo(unsigned w) { return __uint_as_float(w << 16); }
; __device__ __forceinline__ float bfhi(unsigned w) { return __uint_as_float(w & 0xffff0000u); }
; __device__ __forceinline__ float silu_f(float g) { return g * __builtin_amdgcn_rcpf(1.0f + __expf(-g)); }
; __device__ __forceinline__ void conv_phase(const Ctx& c) {
;     ...
; #pragma unroll
;                 for (int i = 0; i < 16; ++i) {
;                     if (samp && (i & 7) == 0) { h0 = sh[i >> 3][0]; h1 = sh[i >> 3][1]; h2 = sh[i >> 3][2]; }
;                     const f32x4 x = (f32x4){bflo(raw[i].x), bfhi(raw[i].x), bflo(raw[i].y), bfhi(raw[i].y)};
;                     f32x4 o = w0 * h0 + w1 * h1 + w2 * h2 + w3 * x + bb;
;                     o[0] = silu_f(o[0]); o[1] = silu_f(o[1]); o[2] = silu_f(o[2]); o[3] = silu_f(o[3]);
;                     u32x2 w; w.x = cvt_pk_bf16(o[0], o[1]); w.y = cvt_pk_bf16(o[2], o[3]);
;                     *(u32x2*)(XBC + (rbase + i) * CONVD + ch) = w;
;                     if (samp) { if ((i & 7) >= 5) *(f32x4*)(cso + ((size_t)(sq + (i >> 3)) * 3 + ((i & 7) - 5)) * CONVD + ch) = x; }
;                     else if (lastp && t0 == 112 && i >= 13) *(f32x4*)(cpo + ((size_t)(ck >> 5) * 3 + (i - 13)) * CONVD + ch) = x;
;                     h0 = h1; h1 = h2; h2 = x;
	v_lshlrev_b32_e32 v56, 16, v114
	v_and_b32_e32 v57, 0xffff0000, v114
	v_pk_fma_f32 v[52:53], v[40:41], v[56:57], v[52:53]
	v_lshlrev_b32_e32 v58, 16, v115
	v_pk_add_f32 v[52:53], v[44:45], v[52:53]
	v_and_b32_e32 v59, 0xffff0000, v115
	v_mul_f32_e32 v3, 0xbfb8aa3b, v52
	v_exp_f32_e32 v3, v3
	v_pk_fma_f32 v[54:55], v[42:43], v[58:59], v[54:55]
	v_lshl_add_u64 v[116:117], v[76:77], 0, s[6:7]
	v_pk_add_f32 v[54:55], v[46:47], v[54:55]
	v_add_f32_e32 v3, 1.0, v3
	v_rcp_f32_e32 v114, v3
	v_mul_f32_e32 v3, 0xbfb8aa3b, v53
	v_exp_f32_e32 v3, v3
	s_mov_b64 s[6:7], 0x1348b000
	v_lshl_add_u64 v[112:113], v[76:77], 0, s[6:7]
	s_mov_b64 s[6:7], 0x1348c800
	v_add_f32_e32 v3, 1.0, v3
	v_rcp_f32_e32 v115, v3
	v_mul_f32_e32 v3, 0xbfb8aa3b, v54
	v_exp_f32_e32 v3, v3
	v_lshl_add_u64 v[108:109], v[76:77], 0, s[6:7]
	v_pk_mul_f32 v[52:53], v[52:53], v[114:115]
	s_mov_b64 s[6:7], 0x1348e000
	v_add_f32_e32 v3, 1.0, v3
	v_rcp_f32_e32 v114, v3
	v_mul_f32_e32 v3, 0xbfb8aa3b, v55
	v_exp_f32_e32 v3, v3
	v_cvt_pk_bf16_f32 v52, v52, v53
	v_lshl_add_u64 v[104:105], v[76:77], 0, s[6:7]
	s_mov_b64 s[6:7], 0x1348f800
	v_add_f32_e32 v3, 1.0, v3
	v_rcp_f32_e32 v115, v3
	v_lshl_add_u64 v[100:101], v[76:77], 0, s[6:7]
	s_and_b64 vcc, exec, s[4:5]
	v_pk_mul_f32 v[54:55], v[54:55], v[114:115]
	v_pk_mul_f32 v[114:115], v[28:29], v[118:119]
	v_cvt_pk_bf16_f32 v53, v54, v55
	v_pk_fma_f32 v[114:115], v[32:33], v[48:49], v[114:115]
	global_store_dwordx2 v[116:117], v[52:53], off
	v_lshlrev_b32_e32 v52, 16, v110
	v_and_b32_e32 v53, 0xffff0000, v110
	v_pk_fma_f32 v[114:115], v[36:37], v[56:57], v[114:115]
	v_lshlrev_b32_e32 v54, 16, v111
	v_pk_fma_f32 v[114:115], v[40:41], v[52:53], v[114:115]
	v_and_b32_e32 v55, 0xffff0000, v111
	v_pk_add_f32 v[114:115], v[44:45], v[114:115]
	v_pk_mul_f32 v[110:111], v[30:31], v[120:121]
	v_mul_f32_e32 v3, 0xbfb8aa3b, v114
	v_exp_f32_e32 v3, v3
	v_pk_fma_f32 v[110:111], v[34:35], v[50:51], v[110:111]
	v_add_f32_e32 v3, 1.0, v3
	v_rcp_f32_e32 v116, v3
	v_mul_f32_e32 v3, 0xbfb8aa3b, v115
	v_exp_f32_e32 v3, v3
	v_pk_fma_f32 v[110:111], v[38:39], v[58:59], v[110:111]
	v_add_f32_e32 v3, 1.0, v3
	v_pk_fma_f32 v[110:111], v[42:43], v[54:55], v[110:111]
	v_rcp_f32_e32 v117, v3
	v_pk_add_f32 v[110:111], v[46:47], v[110:111]
	v_pk_mul_f32 v[114:115], v[114:115], v[116:117]
	v_mul_f32_e32 v3, 0xbfb8aa3b, v110
	v_exp_f32_e32 v3, v3
	v_cvt_pk_bf16_f32 v114, v114, v115
	v_add_f32_e32 v3, 1.0, v3
	v_rcp_f32_e32 v116, v3
	v_mul_f32_e32 v3, 0xbfb8aa3b, v111
	v_exp_f32_e32 v3, v3
	s_nop 0
	v_add_f32_e32 v3, 1.0, v3
	v_rcp_f32_e32 v117, v3
	s_nop 0
	v_pk_mul_f32 v[110:111], v[110:111], v[116:117]
	s_nop 0
	v_cvt_pk_bf16_f32 v115, v110, v111
	global_store_dwordx2 v[112:113], v[114:115], off
	v_pk_mul_f32 v[114:115], v[32:33], v[56:57]
	v_lshlrev_b32_e32 v110, 16, v106
	v_pk_fma_f32 v[48:49], v[28:29], v[48:49], v[114:115]
	v_and_b32_e32 v111, 0xffff0000, v106
	v_pk_fma_f32 v[48:49], v[36:37], v[52:53], v[48:49]
	v_pk_mul_f32 v[112:113], v[34:35], v[58:59]
	v_pk_fma_f32 v[48:49], v[40:41], v[110:111], v[48:49]
	v_pk_fma_f32 v[50:51], v[30:31], v[50:51], v[112:113]
	v_pk_add_f32 v[48:49], v[44:45], v[48:49]
	v_lshlrev_b32_e32 v106, 16, v107
	v_mul_f32_e32 v3, 0xbfb8aa3b, v48
	v_exp_f32_e32 v3, v3
	v_and_b32_e32 v107, 0xffff0000, v107
	v_pk_fma_f32 v[50:51], v[38:39], v[54:55], v[50:51]
	v_add_f32_e32 v3, 1.0, v3
	v_rcp_f32_e32 v112, v3
	v_mul_f32_e32 v3, 0xbfb8aa3b, v49
	v_exp_f32_e32 v3, v3
	v_pk_fma_f32 v[50:51], v[42:43], v[106:107], v[50:51]
	v_add_f32_e32 v3, 1.0, v3
	v_pk_add_f32 v[50:51], v[46:47], v[50:51]
	v_rcp_f32_e32 v113, v3
	v_mul_f32_e32 v3, 0xbfb8aa3b, v50
	v_exp_f32_e32 v3, v3
	v_pk_mul_f32 v[48:49], v[48:49], v[112:113]
	s_nop 0
	v_cvt_pk_bf16_f32 v48, v48, v49
	v_add_f32_e32 v3, 1.0, v3
	v_rcp_f32_e32 v112, v3
	v_mul_f32_e32 v3, 0xbfb8aa3b, v51
	v_exp_f32_e32 v3, v3
	s_nop 0
	v_add_f32_e32 v3, 1.0, v3
	v_rcp_f32_e32 v113, v3
	s_nop 0
	v_pk_mul_f32 v[50:51], v[50:51], v[112:113]
	s_nop 0
	v_cvt_pk_bf16_f32 v49, v50, v51
	v_pk_mul_f32 v[50:51], v[32:33], v[52:53]
	global_store_dwordx2 v[108:109], v[48:49], off
	v_pk_fma_f32 v[50:51], v[28:29], v[56:57], v[50:51]
	v_lshlrev_b32_e32 v108, 16, v102
	v_and_b32_e32 v109, 0xffff0000, v102
	v_pk_fma_f32 v[50:51], v[36:37], v[110:111], v[50:51]
	v_pk_mul_f32 v[48:49], v[34:35], v[54:55]
	v_pk_fma_f32 v[50:51], v[40:41], v[108:109], v[50:51]
	v_pk_fma_f32 v[48:49], v[30:31], v[58:59], v[48:49]
	v_pk_add_f32 v[50:51], v[44:45], v[50:51]
	v_lshlrev_b32_e32 v102, 16, v103
	v_mul_f32_e32 v3, 0xbfb8aa3b, v50
	v_exp_f32_e32 v3, v3
	v_and_b32_e32 v103, 0xffff0000, v103
	v_pk_fma_f32 v[48:49], v[38:39], v[106:107], v[48:49]
	v_lshlrev_b32_e32 v58, 16, v99
	v_add_f32_e32 v3, 1.0, v3
	v_rcp_f32_e32 v56, v3
	v_mul_f32_e32 v3, 0xbfb8aa3b, v51
	v_exp_f32_e32 v3, v3
	v_pk_fma_f32 v[48:49], v[42:43], v[102:103], v[48:49]
	v_and_b32_e32 v59, 0xffff0000, v99
	v_pk_add_f32 v[48:49], v[46:47], v[48:49]
	v_add_f32_e32 v3, 1.0, v3
	v_rcp_f32_e32 v57, v3
	v_mul_f32_e32 v3, 0xbfb8aa3b, v48
	v_exp_f32_e32 v3, v3
	v_pk_mul_f32 v[50:51], v[50:51], v[56:57]
	s_nop 0
	v_cvt_pk_bf16_f32 v50, v50, v51
	v_add_f32_e32 v3, 1.0, v3
	v_rcp_f32_e32 v56, v3
	v_mul_f32_e32 v3, 0xbfb8aa3b, v49
	v_exp_f32_e32 v3, v3
	s_nop 0
	v_add_f32_e32 v3, 1.0, v3
	v_rcp_f32_e32 v57, v3
	s_nop 0
	v_pk_mul_f32 v[48:49], v[48:49], v[56:57]
	s_nop 0
	v_cvt_pk_bf16_f32 v51, v48, v49
	global_store_dwordx2 v[104:105], v[50:51], off
	v_pk_mul_f32 v[50:51], v[32:33], v[110:111]
	v_lshlrev_b32_e32 v56, 16, v98
	v_pk_fma_f32 v[50:51], v[28:29], v[52:53], v[50:51]
	v_and_b32_e32 v57, 0xffff0000, v98
	v_pk_fma_f32 v[50:51], v[36:37], v[108:109], v[50:51]
	v_pk_mul_f32 v[48:49], v[34:35], v[106:107]
	v_pk_fma_f32 v[50:51], v[40:41], v[56:57], v[50:51]
	v_pk_fma_f32 v[48:49], v[30:31], v[54:55], v[48:49]
	v_pk_add_f32 v[50:51], v[44:45], v[50:51]
	v_pk_fma_f32 v[48:49], v[38:39], v[102:103], v[48:49]
	v_mul_f32_e32 v3, 0xbfb8aa3b, v50
	v_exp_f32_e32 v3, v3
	v_pk_fma_f32 v[48:49], v[42:43], v[58:59], v[48:49]
	v_add_f32_e32 v3, 1.0, v3
	v_rcp_f32_e32 v52, v3
	v_mul_f32_e32 v3, 0xbfb8aa3b, v51
	v_exp_f32_e32 v3, v3
	v_pk_add_f32 v[48:49], v[46:47], v[48:49]
	v_add_f32_e32 v3, 1.0, v3
	v_rcp_f32_e32 v53, v3
	v_mul_f32_e32 v3, 0xbfb8aa3b, v48
	v_exp_f32_e32 v3, v3
	v_pk_mul_f32 v[50:51], v[50:51], v[52:53]
	s_nop 0
	v_cvt_pk_bf16_f32 v50, v50, v51
	v_add_f32_e32 v3, 1.0, v3
	v_rcp_f32_e32 v52, v3
	v_mul_f32_e32 v3, 0xbfb8aa3b, v49
	v_exp_f32_e32 v3, v3
	s_nop 0
	v_add_f32_e32 v3, 1.0, v3
	v_rcp_f32_e32 v53, v3
	s_nop 0
	v_pk_mul_f32 v[48:49], v[48:49], v[52:53]
	s_nop 0
	v_cvt_pk_bf16_f32 v51, v48, v49
	global_store_dwordx2 v[100:101], v[50:51], off
	s_cbranch_vccnz .LBB0_250
	v_mad_i64_i32 v[48:49], s[6:7], s25, v235, v[0:1]
	global_store_dwordx4 v[48:49], v[56:59], off

; __device__ __forceinline__ unsigned cvt_pk_bf16(float lo, float hi) { f32x2 v = {lo, hi}; bf16x2_t b = __builtin_convertvector(v, bf16x2_t); return __builtin_bit_cast(unsigned, b); }
; __device__ __forceinline__ float bflo(unsigned w) { return __uint_as_float(w << 16); }
; __device__ __forceinline__ float bfhi(unsigned w) { return __uint_as_float(w & 0xffff0000u); }
; __device__ __forceinline__ float silu_f(float g) { return g * __builtin_amdgcn_rcpf(1.0f + __expf(-g)); }
; __device__ __forceinline__ void conv_phase(const Ctx& c) {
;     ...
; #pragma unroll
;                 for (int i = 0; i < 16; ++i) {
;                     if (samp && (i & 7) == 0) { h0 = sh[i >> 3][0]; h1 = sh[i >> 3][1]; h2 = sh[i >> 3][2]; }
;                     const f32x4 x = (f32x4){bflo(raw[i].x), bfhi(raw[i].x), bflo(raw[i].y), bfhi(raw[i].y)};
;                     f32x4 o = w0 * h0 + w1 * h1 + w2 * h2 + w3 * x + bb;
;                     o[0] = silu_f(o[0]); o[1] = silu_f(o[1]); o[2] = silu_f(o[2]); o[3] = silu_f(o[3]);
;                     u32x2 w; w.x = cvt_pk_bf16(o[0], o[1]); w.y = cvt_pk_bf16(o[2], o[3]);
;                     *(u32x2*)(XBC + (rbase + i) * CONVD + ch) = w;
;                     if (samp) { if ((i & 7) >= 5) *(f32x4*)(cso + ((size_t)(sq + (i >> 3)) * 3 + ((i & 7) - 5)) * CONVD + ch) = x; }
;                     else if (lastp && t0 == 112 && i >= 13) *(f32x4*)(cpo + ((size_t)(ck >> 5) * 3 + (i - 13)) * CONVD + ch) = x;
;                     h0 = h1; h1 = h2; h2 = x;
.LBB0_254:
	v_pk_mul_f32 v[56:57], v[28:29], v[56:57]
	v_lshlrev_b32_e32 v102, 16, v92
	v_pk_fma_f32 v[56:57], v[32:33], v[52:53], v[56:57]
	v_and_b32_e32 v103, 0xffff0000, v92
	v_pk_fma_f32 v[56:57], v[36:37], v[48:49], v[56:57]
	v_pk_mul_f32 v[58:59], v[30:31], v[58:59]
	v_pk_fma_f32 v[56:57], v[40:41], v[102:103], v[56:57]
	v_pk_fma_f32 v[58:59], v[34:35], v[54:55], v[58:59]
	v_pk_add_f32 v[56:57], v[44:45], v[56:57]
	v_lshlrev_b32_e32 v92, 16, v93
	v_mul_f32_e32 v3, 0xbfb8aa3b, v56
	v_exp_f32_e32 v3, v3
	v_and_b32_e32 v93, 0xffff0000, v93
	v_pk_fma_f32 v[58:59], v[38:39], v[50:51], v[58:59]
	s_mov_b64 s[4:5], 0x13494000
	v_add_f32_e32 v3, 1.0, v3
	v_rcp_f32_e32 v108, v3
	v_mul_f32_e32 v3, 0xbfb8aa3b, v57
	v_exp_f32_e32 v3, v3
	v_pk_fma_f32 v[58:59], v[42:43], v[92:93], v[58:59]
	v_pk_mul_f32 v[52:53], v[28:29], v[52:53]
	v_pk_add_f32 v[58:59], v[46:47], v[58:59]
	v_add_f32_e32 v3, 1.0, v3
	v_rcp_f32_e32 v109, v3
	v_mul_f32_e32 v3, 0xbfb8aa3b, v58
	v_exp_f32_e32 v3, v3
	v_lshl_add_u64 v[104:105], v[76:77], 0, s[4:5]
	v_pk_mul_f32 v[56:57], v[56:57], v[108:109]
	v_pk_fma_f32 v[52:53], v[32:33], v[48:49], v[52:53]
	v_add_f32_e32 v3, 1.0, v3
	v_rcp_f32_e32 v108, v3
	v_mul_f32_e32 v3, 0xbfb8aa3b, v59
	v_exp_f32_e32 v3, v3
	v_cvt_pk_bf16_f32 v56, v56, v57
	v_pk_fma_f32 v[52:53], v[36:37], v[102:103], v[52:53]
	v_pk_mul_f32 v[54:55], v[30:31], v[54:55]
	v_add_f32_e32 v3, 1.0, v3
	v_rcp_f32_e32 v109, v3
	v_pk_fma_f32 v[54:55], v[34:35], v[50:51], v[54:55]
	s_mov_b64 s[4:5], 0x13495800
	v_pk_fma_f32 v[54:55], v[38:39], v[92:93], v[54:55]
	v_pk_mul_f32 v[58:59], v[58:59], v[108:109]
	v_pk_mul_f32 v[48:49], v[28:29], v[48:49]
	v_cvt_pk_bf16_f32 v57, v58, v59
	global_store_dwordx2 v[104:105], v[56:57], off
	v_lshlrev_b32_e32 v104, 16, v90
	v_and_b32_e32 v105, 0xffff0000, v90
	v_pk_fma_f32 v[52:53], v[40:41], v[104:105], v[52:53]
	v_lshlrev_b32_e32 v90, 16, v91
	v_pk_add_f32 v[52:53], v[44:45], v[52:53]
	v_and_b32_e32 v91, 0xffff0000, v91
	v_mul_f32_e32 v3, 0xbfb8aa3b, v52
	v_exp_f32_e32 v3, v3
	v_pk_fma_f32 v[54:55], v[42:43], v[90:91], v[54:55]
	v_lshl_add_u64 v[106:107], v[76:77], 0, s[4:5]
	v_pk_add_f32 v[54:55], v[46:47], v[54:55]
	v_add_f32_e32 v3, 1.0, v3
	v_rcp_f32_e32 v56, v3
	v_mul_f32_e32 v3, 0xbfb8aa3b, v53
	v_exp_f32_e32 v3, v3
	v_pk_fma_f32 v[48:49], v[32:33], v[102:103], v[48:49]
	v_pk_mul_f32 v[50:51], v[30:31], v[50:51]
	v_pk_fma_f32 v[48:49], v[36:37], v[104:105], v[48:49]
	v_add_f32_e32 v3, 1.0, v3
	v_rcp_f32_e32 v57, v3
	v_mul_f32_e32 v3, 0xbfb8aa3b, v54
	v_exp_f32_e32 v3, v3
	v_pk_fma_f32 v[50:51], v[34:35], v[92:93], v[50:51]
	v_pk_mul_f32 v[52:53], v[52:53], v[56:57]
	v_pk_fma_f32 v[50:51], v[38:39], v[90:91], v[50:51]
	v_add_f32_e32 v3, 1.0, v3
	v_rcp_f32_e32 v56, v3
	v_mul_f32_e32 v3, 0xbfb8aa3b, v55
	v_exp_f32_e32 v3, v3
	v_cvt_pk_bf16_f32 v52, v52, v53
	s_mov_b64 s[4:5], 0x13497000
	v_lshl_add_u64 v[100:101], v[76:77], 0, s[4:5]
	v_add_f32_e32 v3, 1.0, v3
	v_rcp_f32_e32 v57, v3
	v_lshlrev_b32_e32 v58, 16, v87
	v_and_b32_e32 v59, 0xffff0000, v87
	s_mov_b64 s[4:5], 0x13498800
	v_pk_mul_f32 v[54:55], v[54:55], v[56:57]
	v_lshl_add_u64 v[98:99], v[76:77], 0, s[4:5]
	v_cvt_pk_bf16_f32 v53, v54, v55
	global_store_dwordx2 v[106:107], v[52:53], off
	v_lshlrev_b32_e32 v52, 16, v88
	v_and_b32_e32 v53, 0xffff0000, v88
	v_pk_fma_f32 v[48:49], v[40:41], v[52:53], v[48:49]
	v_lshlrev_b32_e32 v54, 16, v89
	v_pk_add_f32 v[48:49], v[44:45], v[48:49]
	v_and_b32_e32 v55, 0xffff0000, v89
	v_mul_f32_e32 v3, 0xbfb8aa3b, v48
	v_exp_f32_e32 v3, v3
	v_pk_fma_f32 v[50:51], v[42:43], v[54:55], v[50:51]
	s_mov_b64 s[4:5], 0x1349a000
	v_pk_add_f32 v[50:51], v[46:47], v[50:51]
	v_add_f32_e32 v3, 1.0, v3
	v_rcp_f32_e32 v56, v3
	v_mul_f32_e32 v3, 0xbfb8aa3b, v49
	v_exp_f32_e32 v3, v3
	v_lshl_add_u64 v[96:97], v[76:77], 0, s[4:5]
	s_mov_b64 s[4:5], 0x1349b800
	s_cmp_eq_u32 s16, 0xa8000
	v_add_f32_e32 v3, 1.0, v3
	v_rcp_f32_e32 v57, v3
	v_mul_f32_e32 v3, 0xbfb8aa3b, v50
	v_exp_f32_e32 v3, v3
	v_lshl_add_u64 v[94:95], v[76:77], 0, s[4:5]
	v_pk_mul_f32 v[48:49], v[48:49], v[56:57]
	s_cselect_b64 s[4:5], -1, 0
	v_add_f32_e32 v3, 1.0, v3
	v_rcp_f32_e32 v56, v3
	v_mul_f32_e32 v3, 0xbfb8aa3b, v51
	v_exp_f32_e32 v3, v3
	v_cvt_pk_bf16_f32 v48, v48, v49
	s_and_b64 s[6:7], s[14:15], s[4:5]
	s_mov_b64 s[18:19], -1
	v_add_f32_e32 v3, 1.0, v3
; __device__ __forceinline__ unsigned cvt_pk_bf16(float lo, float hi) { f32x2 v = {lo, hi}; bf16x2_t b = __builtin_convertvector(v, bf16x2_t); return __builtin_bit_cast(unsigned, b); }
; __device__ __forceinline__ float bflo(unsigned w) { return __uint_as_float(w << 16); }
; __device__ __forceinline__ float bfhi(unsigned w) { return __uint_as_float(w & 0xffff0000u); }
; __device__ __forceinline__ float silu_f(float g) { return g * __builtin_amdgcn_rcpf(1.0f + __expf(-g)); }
; __device__ __forceinline__ void conv_phase(const Ctx& c) {
;     ...
; #pragma unroll
;                 for (int i = 0; i < 16; ++i) {
;                     if (samp && (i & 7) == 0) { h0 = sh[i >> 3][0]; h1 = sh[i >> 3][1]; h2 = sh[i >> 3][2]; }
;                     const f32x4 x = (f32x4){bflo(raw[i].x), bfhi(raw[i].x), bflo(raw[i].y), bfhi(raw[i].y)};
;                     f32x4 o = w0 * h0 + w1 * h1 + w2 * h2 + w3 * x + bb;
;                     o[0] = silu_f(o[0]); o[1] = silu_f(o[1]); o[2] = silu_f(o[2]); o[3] = silu_f(o[3]);
;                     u32x2 w; w.x = cvt_pk_bf16(o[0], o[1]); w.y = cvt_pk_bf16(o[2], o[3]);
;                     *(u32x2*)(XBC + (rbase + i) * CONVD + ch) = w;
;                     if (samp) { if ((i & 7) >= 5) *(f32x4*)(cso + ((size_t)(sq + (i >> 3)) * 3 + ((i & 7) - 5)) * CONVD + ch) = x; }
;                     else if (lastp && t0 == 112 && i >= 13) *(f32x4*)(cpo + ((size_t)(ck >> 5) * 3 + (i - 13)) * CONVD + ch) = x;
;                     h0 = h1; h1 = h2; h2 = x;
	v_rcp_f32_e32 v57, v3
	s_andn2_b64 vcc, exec, s[12:13]
	v_pk_mul_f32 v[50:51], v[50:51], v[56:57]
	s_nop 0
	v_cvt_pk_bf16_f32 v49, v50, v51
	v_pk_mul_f32 v[50:51], v[32:33], v[104:105]
	v_lshlrev_b32_e32 v56, 16, v86
	v_pk_fma_f32 v[50:51], v[28:29], v[102:103], v[50:51]
	v_and_b32_e32 v57, 0xffff0000, v86
	v_pk_fma_f32 v[50:51], v[36:37], v[52:53], v[50:51]
	global_store_dwordx2 v[100:101], v[48:49], off
	v_pk_fma_f32 v[50:51], v[40:41], v[56:57], v[50:51]
	v_pk_mul_f32 v[48:49], v[34:35], v[90:91]
	v_pk_add_f32 v[50:51], v[44:45], v[50:51]
	v_pk_fma_f32 v[48:49], v[30:31], v[92:93], v[48:49]
	v_mul_f32_e32 v3, 0xbfb8aa3b, v50
	v_exp_f32_e32 v3, v3
	v_pk_fma_f32 v[48:49], v[38:39], v[54:55], v[48:49]
	v_add_f32_e32 v3, 1.0, v3
	v_rcp_f32_e32 v86, v3
	v_mul_f32_e32 v3, 0xbfb8aa3b, v51
	v_exp_f32_e32 v3, v3
	v_pk_fma_f32 v[48:49], v[42:43], v[58:59], v[48:49]
	v_add_f32_e32 v3, 1.0, v3
	v_pk_add_f32 v[48:49], v[46:47], v[48:49]
	v_rcp_f32_e32 v87, v3
	v_mul_f32_e32 v3, 0xbfb8aa3b, v48
	v_exp_f32_e32 v3, v3
	v_pk_mul_f32 v[50:51], v[50:51], v[86:87]
	s_nop 0
	v_cvt_pk_bf16_f32 v50, v50, v51
	v_add_f32_e32 v3, 1.0, v3
	v_rcp_f32_e32 v86, v3
	v_mul_f32_e32 v3, 0xbfb8aa3b, v49
	v_exp_f32_e32 v3, v3
	s_nop 0
	v_add_f32_e32 v3, 1.0, v3
	v_rcp_f32_e32 v87, v3
	s_nop 0
	v_pk_mul_f32 v[48:49], v[48:49], v[86:87]
	s_nop 0
	v_cvt_pk_bf16_f32 v51, v48, v49
	global_store_dwordx2 v[98:99], v[50:51], off
	v_pk_mul_f32 v[50:51], v[32:33], v[52:53]
	v_lshlrev_b32_e32 v86, 16, v84
	v_pk_fma_f32 v[50:51], v[28:29], v[104:105], v[50:51]
	v_and_b32_e32 v87, 0xffff0000, v84
	v_pk_fma_f32 v[50:51], v[36:37], v[56:57], v[50:51]
	v_pk_mul_f32 v[48:49], v[34:35], v[54:55]
	v_pk_fma_f32 v[50:51], v[40:41], v[86:87], v[50:51]
	v_pk_fma_f32 v[48:49], v[30:31], v[90:91], v[48:49]
	v_pk_add_f32 v[50:51], v[44:45], v[50:51]
	v_lshlrev_b32_e32 v84, 16, v85
	v_mul_f32_e32 v3, 0xbfb8aa3b, v50
	v_exp_f32_e32 v3, v3
	v_and_b32_e32 v85, 0xffff0000, v85
	v_pk_fma_f32 v[48:49], v[38:39], v[58:59], v[48:49]
	v_add_f32_e32 v3, 1.0, v3
	v_rcp_f32_e32 v88, v3
	v_mul_f32_e32 v3, 0xbfb8aa3b, v51
	v_exp_f32_e32 v3, v3
	v_pk_fma_f32 v[48:49], v[42:43], v[84:85], v[48:49]
	v_add_f32_e32 v3, 1.0, v3
	v_pk_add_f32 v[48:49], v[46:47], v[48:49]
	v_rcp_f32_e32 v89, v3
	v_mul_f32_e32 v3, 0xbfb8aa3b, v48
	v_exp_f32_e32 v3, v3
	v_pk_mul_f32 v[50:51], v[50:51], v[88:89]
	s_nop 0
	v_cvt_pk_bf16_f32 v50, v50, v51
	v_add_f32_e32 v3, 1.0, v3
	v_rcp_f32_e32 v88, v3
	v_mul_f32_e32 v3, 0xbfb8aa3b, v49
	v_exp_f32_e32 v3, v3
	s_nop 0
	v_add_f32_e32 v3, 1.0, v3
	v_rcp_f32_e32 v89, v3
	s_nop 0
	v_pk_mul_f32 v[48:49], v[48:49], v[88:89]
	v_pk_mul_f32 v[88:89], v[32:33], v[56:57]
	v_cvt_pk_bf16_f32 v51, v48, v49
	v_pk_fma_f32 v[52:53], v[28:29], v[52:53], v[88:89]
	s_cmp_lg_u64 s[2:3], 0
	s_cbranch_scc0 .Lconv_nw1
	s_waitcnt vmcnt(14)
.Lconv_nw1:
	v_lshlrev_b32_e32 v48, 16, v82
	v_and_b32_e32 v49, 0xffff0000, v82
	v_pk_fma_f32 v[52:53], v[36:37], v[86:87], v[52:53]
	global_store_dwordx2 v[96:97], v[50:51], off
	v_pk_fma_f32 v[52:53], v[40:41], v[48:49], v[52:53]
	v_lshlrev_b32_e32 v50, 16, v83
	v_pk_add_f32 v[52:53], v[44:45], v[52:53]
	v_and_b32_e32 v51, 0xffff0000, v83
	v_mul_f32_e32 v3, 0xbfb8aa3b, v52
	v_exp_f32_e32 v3, v3
	v_pk_mul_f32 v[82:83], v[34:35], v[58:59]
	v_add_f32_e32 v3, 1.0, v3
	v_pk_fma_f32 v[54:55], v[30:31], v[54:55], v[82:83]
	v_rcp_f32_e32 v82, v3
	v_mul_f32_e32 v3, 0xbfb8aa3b, v53
	v_exp_f32_e32 v3, v3
	v_pk_fma_f32 v[54:55], v[38:39], v[84:85], v[54:55]
	v_add_f32_e32 v3, 1.0, v3
	v_pk_fma_f32 v[54:55], v[42:43], v[50:51], v[54:55]
	v_rcp_f32_e32 v83, v3
	v_pk_add_f32 v[54:55], v[46:47], v[54:55]
	v_pk_mul_f32 v[52:53], v[52:53], v[82:83]
	v_mul_f32_e32 v3, 0xbfb8aa3b, v54
	v_exp_f32_e32 v3, v3
	v_cvt_pk_bf16_f32 v52, v52, v53
	v_add_f32_e32 v3, 1.0, v3
	v_rcp_f32_e32 v82, v3
	v_mul_f32_e32 v3, 0xbfb8aa3b, v55
	v_exp_f32_e32 v3, v3
	s_nop 0
	v_add_f32_e32 v3, 1.0, v3
	v_rcp_f32_e32 v83, v3
	v_cndmask_b32_e64 v3, 0, 1, s[12:13]
	v_cmp_ne_u32_e64 s[4:5], 1, v3
	v_cndmask_b32_e64 v3, 0, 1, s[6:7]
	v_pk_mul_f32 v[54:55], v[54:55], v[82:83]
	v_cmp_ne_u32_e64 s[6:7], 1, v3
	v_cvt_pk_bf16_f32 v53, v54, v55
	global_store_dwordx2 v[94:95], v[52:53], off
	s_cbranch_vccnz .LBB0_258
	s_and_b64 vcc, exec, s[6:7]
	s_cbranch_vccnz .LBB0_257
	global_store_dwordx4 v[66:67], v[48:51], off

; __device__ __forceinline__ unsigned cvt_pk_bf16(float lo, float hi) { f32x2 v = {lo, hi}; bf16x2_t b = __builtin_convertvector(v, bf16x2_t); return __builtin_bit_cast(unsigned, b); }
; __device__ __forceinline__ float bflo(unsigned w) { return __uint_as_float(w << 16); }
; __device__ __forceinline__ float bfhi(unsigned w) { return __uint_as_float(w & 0xffff0000u); }
; __device__ __forceinline__ float silu_f(float g) { return g * __builtin_amdgcn_rcpf(1.0f + __expf(-g)); }
; __device__ __forceinline__ void conv_phase(const Ctx& c) {
;     ...
; #pragma unroll
;                 for (int i = 0; i < 16; ++i) {
;                     if (samp && (i & 7) == 0) { h0 = sh[i >> 3][0]; h1 = sh[i >> 3][1]; h2 = sh[i >> 3][2]; }
;                     const f32x4 x = (f32x4){bflo(raw[i].x), bfhi(raw[i].x), bflo(raw[i].y), bfhi(raw[i].y)};
;                     f32x4 o = w0 * h0 + w1 * h1 + w2 * h2 + w3 * x + bb;
;                     o[0] = silu_f(o[0]); o[1] = silu_f(o[1]); o[2] = silu_f(o[2]); o[3] = silu_f(o[3]);
;                     u32x2 w; w.x = cvt_pk_bf16(o[0], o[1]); w.y = cvt_pk_bf16(o[2], o[3]);
;                     *(u32x2*)(XBC + (rbase + i) * CONVD + ch) = w;
;                     if (samp) { if ((i & 7) >= 5) *(f32x4*)(cso + ((size_t)(sq + (i >> 3)) * 3 + ((i & 7) - 5)) * CONVD + ch) = x; }
;                     else if (lastp && t0 == 112 && i >= 13) *(f32x4*)(cpo + ((size_t)(ck >> 5) * 3 + (i - 13)) * CONVD + ch) = x;
;                     h0 = h1; h1 = h2; h2 = x;
.LBB0_260:
	v_pk_mul_f32 v[82:83], v[32:33], v[86:87]
	s_cmp_lg_u64 s[2:3], 0
	s_cbranch_scc0 .Lconv_nw2
	s_waitcnt vmcnt(15)
.Lconv_nw2:
	v_lshlrev_b32_e32 v52, 16, v80
	v_pk_fma_f32 v[56:57], v[28:29], v[56:57], v[82:83]
	v_and_b32_e32 v53, 0xffff0000, v80
	v_pk_fma_f32 v[56:57], v[36:37], v[48:49], v[56:57]
	v_lshlrev_b32_e32 v54, 16, v81
	v_pk_fma_f32 v[56:57], v[40:41], v[52:53], v[56:57]
	v_and_b32_e32 v55, 0xffff0000, v81
	v_pk_add_f32 v[56:57], v[44:45], v[56:57]
	v_pk_mul_f32 v[80:81], v[34:35], v[84:85]
	v_mul_f32_e32 v3, 0xbfb8aa3b, v56
	v_exp_f32_e32 v3, v3
	v_mul_f32_e32 v65, 0xbfb8aa3b, v57
	v_pk_fma_f32 v[58:59], v[30:31], v[58:59], v[80:81]
	v_exp_f32_e32 v65, v65
	v_pk_fma_f32 v[58:59], v[38:39], v[50:51], v[58:59]
	v_add_f32_e32 v3, 1.0, v3
	v_pk_fma_f32 v[58:59], v[42:43], v[54:55], v[58:59]
	v_rcp_f32_e32 v80, v3
	v_pk_add_f32 v[58:59], v[46:47], v[58:59]
	v_add_f32_e32 v3, 1.0, v65
	v_mul_f32_e32 v65, 0xbfb8aa3b, v58
	v_exp_f32_e32 v65, v65
	v_mul_f32_e32 v81, 0xbfb8aa3b, v59
	v_exp_f32_e32 v83, v81
	v_rcp_f32_e32 v81, v3
	v_add_f32_e32 v3, 1.0, v65
	v_rcp_f32_e32 v82, v3
	v_add_f32_e32 v3, 1.0, v83
	v_rcp_f32_e32 v83, v3
	s_mov_b64 s[18:19], 0x1349d000
	v_pk_mul_f32 v[56:57], v[56:57], v[80:81]
	v_lshl_add_u64 v[88:89], v[76:77], 0, s[18:19]
	v_pk_mul_f32 v[58:59], v[58:59], v[82:83]
	v_cvt_pk_bf16_f32 v56, v56, v57
	v_cvt_pk_bf16_f32 v57, v58, v59
	s_and_b64 vcc, exec, s[4:5]
	s_mov_b64 s[18:19], -1
	global_store_dwordx2 v[88:89], v[56:57], off
	s_cbranch_vccnz .LBB0_264
	s_and_b64 vcc, exec, s[6:7]
	s_cbranch_vccnz .LBB0_263
	global_store_dwordx4 v[68:69], v[52:55], off

; __device__ __forceinline__ unsigned cvt_pk_bf16(float lo, float hi) { f32x2 v = {lo, hi}; bf16x2_t b = __builtin_convertvector(v, bf16x2_t); return __builtin_bit_cast(unsigned, b); }
; __device__ __forceinline__ float bflo(unsigned w) { return __uint_as_float(w << 16); }
; __device__ __forceinline__ float bfhi(unsigned w) { return __uint_as_float(w & 0xffff0000u); }
; __device__ __forceinline__ float silu_f(float g) { return g * __builtin_amdgcn_rcpf(1.0f + __expf(-g)); }
; __device__ __forceinline__ void conv_phase(const Ctx& c) {
;     ...
; #pragma unroll
;                 for (int i = 0; i < 16; ++i) {
;                     if (samp && (i & 7) == 0) { h0 = sh[i >> 3][0]; h1 = sh[i >> 3][1]; h2 = sh[i >> 3][2]; }
;                     const f32x4 x = (f32x4){bflo(raw[i].x), bfhi(raw[i].x), bflo(raw[i].y), bfhi(raw[i].y)};
;                     f32x4 o = w0 * h0 + w1 * h1 + w2 * h2 + w3 * x + bb;
;                     o[0] = silu_f(o[0]); o[1] = silu_f(o[1]); o[2] = silu_f(o[2]); o[3] = silu_f(o[3]);
;                     u32x2 w; w.x = cvt_pk_bf16(o[0], o[1]); w.y = cvt_pk_bf16(o[2], o[3]);
;                     *(u32x2*)(XBC + (rbase + i) * CONVD + ch) = w;
;                     if (samp) { if ((i & 7) >= 5) *(f32x4*)(cso + ((size_t)(sq + (i >> 3)) * 3 + ((i & 7) - 5)) * CONVD + ch) = x; }
;                     else if (lastp && t0 == 112 && i >= 13) *(f32x4*)(cpo + ((size_t)(ck >> 5) * 3 + (i - 13)) * CONVD + ch) = x;
;                     h0 = h1; h1 = h2; h2 = x;
.LBB0_266:
	v_pk_mul_f32 v[80:81], v[32:33], v[48:49]
	s_cmp_lg_u64 s[2:3], 0
	s_cbranch_scc0 .Lconv_nw3
	s_waitcnt vmcnt(15)
.Lconv_nw3:
	v_lshlrev_b32_e32 v56, 16, v78
	v_pk_fma_f32 v[80:81], v[28:29], v[86:87], v[80:81]
	v_and_b32_e32 v57, 0xffff0000, v78
	v_pk_fma_f32 v[80:81], v[36:37], v[52:53], v[80:81]
	v_lshlrev_b32_e32 v58, 16, v79
	v_pk_fma_f32 v[80:81], v[40:41], v[56:57], v[80:81]
	v_and_b32_e32 v59, 0xffff0000, v79
	v_pk_add_f32 v[80:81], v[44:45], v[80:81]
	v_pk_mul_f32 v[78:79], v[34:35], v[50:51]
	v_mul_f32_e32 v3, 0xbfb8aa3b, v80
	v_exp_f32_e32 v3, v3
	v_mul_f32_e32 v65, 0xbfb8aa3b, v81
	v_pk_fma_f32 v[78:79], v[30:31], v[84:85], v[78:79]
	v_exp_f32_e32 v65, v65
	v_pk_fma_f32 v[78:79], v[38:39], v[54:55], v[78:79]
	v_add_f32_e32 v3, 1.0, v3
	v_pk_fma_f32 v[78:79], v[42:43], v[58:59], v[78:79]
	v_rcp_f32_e32 v82, v3
	v_pk_add_f32 v[78:79], v[46:47], v[78:79]
	v_add_f32_e32 v3, 1.0, v65
	v_mul_f32_e32 v65, 0xbfb8aa3b, v78
	v_exp_f32_e32 v65, v65
	v_mul_f32_e32 v83, 0xbfb8aa3b, v79
	v_exp_f32_e32 v85, v83
	v_rcp_f32_e32 v83, v3
	v_add_f32_e32 v3, 1.0, v65
	v_rcp_f32_e32 v84, v3
	v_add_f32_e32 v3, 1.0, v85
	v_rcp_f32_e32 v85, v3
	s_mov_b64 s[18:19], 0x1349e800
	v_pk_mul_f32 v[80:81], v[80:81], v[82:83]
	v_lshl_add_u64 v[76:77], v[76:77], 0, s[18:19]
	v_pk_mul_f32 v[78:79], v[78:79], v[84:85]
	v_cvt_pk_bf16_f32 v80, v80, v81
	v_cvt_pk_bf16_f32 v81, v78, v79
	s_and_b64 vcc, exec, s[4:5]
	s_mov_b64 s[4:5], -1
	global_store_dwordx2 v[76:77], v[80:81], off
	s_cbranch_vccnz .LBB0_270
	s_and_b64 vcc, exec, s[6:7]
	s_cbranch_vccnz .LBB0_269
	global_store_dwordx4 v[70:71], v[56:59], off
